# DSA selection: exact candidate threshold search starts at the common binary prefix of the prefilter threshold and the largest candidate key (skips the leading bit iterations)
# baseline (speedup 1.0000x reference)
.LBB0_2424:
	s_add_i32 s6, s56, 63
	s_lshr_b32 s57, s6, 6
	v_cmp_gt_u32_e64 s[10:11], s56, v186
	v_cmp_gt_u32_e64 s[8:9], s56, v194
	v_cmp_gt_u32_e64 s[6:7], s56, v195
	s_waitcnt lgkmcnt(0)
	v_cndmask_b32_e64 v17, 0, v2, s[10:11]
	v_cndmask_b32_e64 v3, 0, v3, s[8:9]
	v_cndmask_b32_e64 v2, 0, v18, s[6:7]
	v_max3_u32 v19, v17, v3, v2
	v_max3_u32 v19, v19, v16, v15
	v_max3_u32 v19, v19, v14, v13
	v_max3_u32 v19, v19, v12, v11
	v_max3_u32 v19, v19, v10, v9
	v_max3_u32 v19, v19, v8, v7
	v_max3_u32 v19, v19, v6, v5
	v_max_u32_e32 v19, v19, v4
	s_nop 1
	v_max_u32_dpp v19, v19, v19 quad_perm:[1,0,3,2] row_mask:0xf bank_mask:0xf bound_ctrl:1
	s_nop 1
	v_max_u32_dpp v19, v19, v19 quad_perm:[2,3,0,1] row_mask:0xf bank_mask:0xf bound_ctrl:1
	s_nop 1
	v_max_u32_dpp v19, v19, v19 row_half_mirror row_mask:0xf bank_mask:0xf bound_ctrl:1
	s_nop 1
	v_max_u32_dpp v19, v19, v19 row_mirror row_mask:0xf bank_mask:0xf bound_ctrl:1
	s_nop 1
	v_readlane_b32 s6, v19, 0
	v_readlane_b32 s7, v19, 16
	v_readlane_b32 s8, v19, 32
	v_readlane_b32 s9, v19, 48
	s_nop 1
	s_max_u32 s6, s6, s7
	s_max_u32 s8, s8, s9
	s_max_u32 s6, s6, s8
	v_readfirstlane_b32 s7, v223
	s_nop 1
	s_xor_b32 s8, s6, s7
	s_flbit_i32_b32 s9, s8
	s_cmp_eq_u32 s8, 0
	s_cselect_b32 s9, 31, s9
	s_sub_i32 s9, 31, s9
	s_lshl_b32 s8, 2, s9
	s_sub_i32 s8, s8, 1
	s_andn2_b32 s7, s7, s8
	v_mov_b32_e32 v0, s7
	v_mov_b32_e32 v18, s9
	s_branch .LBB0_2426
